# mLSTM chunk loop: gate-scan load narrowed to dwordx3 so a temp no longer aliases its 4th dword; its vmcnt wait moved from right after issue to the first consumer
# baseline (speedup 1.0000x reference)
.LBB0_642:
	s_or_b64 exec, exec, s[26:27]
	v_mov_b32_e32 v12, s52
	v_add_f32_e32 v12, s51, v12
	v_add_f32_e32 v34, s51, v75
	v_max_f32_e32 v75, v34, v12
	v_add_f32_e32 v12, s51, v13
	v_sub_f32_e32 v12, v12, v75
	v_mul_f32_e32 v12, 0x3fb8aa3b, v12
	v_exp_f32_e32 v12, v12
	s_waitcnt vmcnt(4)
	ds_write_b128 v76, v[20:23]
	ds_write_b128 v76, v[16:19] offset:16
	s_waitcnt vmcnt(2)
	ds_write_b128 v76, v[8:11] offset:17408
	ds_write_b128 v76, v[0:3] offset:17424
	v_lshlrev_b32_e32 v13, 16, v8
	v_and_b32_e32 v8, 0xffff0000, v8
	v_mul_f32_e32 v8, v12, v8
	v_cvt_pk_bf16_f32 v8, v8, s0
	ds_write_b16 v73, v8 offset:34960
	v_lshlrev_b32_e32 v8, 16, v9
	v_mul_f32_e32 v8, v12, v8
	v_cvt_pk_bf16_f32 v8, v8, s0
	ds_write_b16 v73, v8 offset:35104
	v_and_b32_e32 v8, 0xffff0000, v9
	v_mul_f32_e32 v8, v12, v8
	v_cvt_pk_bf16_f32 v8, v8, s0
	ds_write_b16 v73, v8 offset:35248
	v_lshlrev_b32_e32 v8, 16, v10
	v_mul_f32_e32 v8, v12, v8
	v_cvt_pk_bf16_f32 v8, v8, s0
	ds_write_b16 v73, v8 offset:35392
	v_and_b32_e32 v8, 0xffff0000, v10
	v_mul_f32_e32 v8, v12, v8
	v_cvt_pk_bf16_f32 v8, v8, s0
	ds_write_b16 v73, v8 offset:35536
	v_lshlrev_b32_e32 v8, 16, v11
	v_mul_f32_e32 v8, v12, v8
	v_cvt_pk_bf16_f32 v8, v8, s0
	ds_write_b16 v73, v8 offset:35680
	v_and_b32_e32 v8, 0xffff0000, v11
	v_mul_f32_e32 v8, v12, v8
	v_cvt_pk_bf16_f32 v8, v8, s0
	ds_write_b16 v73, v8 offset:35824
	v_lshlrev_b32_e32 v8, 16, v0
	v_and_b32_e32 v0, 0xffff0000, v0
	v_mul_f32_e32 v0, v12, v0
	v_cvt_pk_bf16_f32 v0, v0, s0
	ds_write_b16 v74, v0 offset:36112
	v_lshlrev_b32_e32 v0, 16, v1
	v_mul_f32_e32 v0, v12, v0
	v_cvt_pk_bf16_f32 v0, v0, s0
	ds_write_b16 v74, v0 offset:36256
	v_and_b32_e32 v0, 0xffff0000, v1
	v_mul_f32_e32 v0, v12, v0
	v_cvt_pk_bf16_f32 v0, v0, s0
	ds_write_b16 v74, v0 offset:36400
	v_lshlrev_b32_e32 v0, 16, v2
	v_mul_f32_e32 v0, v12, v0
	v_cvt_pk_bf16_f32 v0, v0, s0
	ds_write_b16 v74, v0 offset:36544
	v_and_b32_e32 v0, 0xffff0000, v2
	v_mul_f32_e32 v0, v12, v0
	v_cvt_pk_bf16_f32 v0, v0, s0
	ds_write_b16 v74, v0 offset:36688
	v_lshlrev_b32_e32 v0, 16, v3
	v_mul_f32_e32 v0, v12, v0
	v_cvt_pk_bf16_f32 v0, v0, s0
	ds_write_b16 v74, v0 offset:36832
	v_and_b32_e32 v0, 0xffff0000, v3
	v_mul_f32_e32 v0, v12, v0
	s_mulk_i32 s25, 0x1b00
	v_mul_f32_e32 v13, v12, v13
	v_mul_f32_e32 v8, v12, v8
	v_cvt_pk_bf16_f32 v0, v0, s0
	v_cvt_pk_bf16_f32 v13, v13, s0
	v_cvt_pk_bf16_f32 v8, v8, s0
	ds_write_b16 v74, v0 offset:36976
	v_add_u32_e32 v0, s25, v77
	v_ashrrev_i32_e32 v65, 31, v64
	ds_write_b16 v73, v13 offset:34816
	ds_write_b16 v74, v8 offset:35968
	s_waitcnt vmcnt(1)
	ds_write_b16 v0, v48 offset:53248
	ds_write_b16_d16_hi v0, v48 offset:53392
	ds_write_b16 v0, v49 offset:53536
	ds_write_b16_d16_hi v0, v49 offset:53680
	v_lshlrev_b64 v[0:1], 11, v[64:65]
	v_lshl_add_u64 v[8:9], v[58:59], 0, v[0:1]
	global_load_dwordx3 v[12:14], v[62:63], off
	global_load_dwordx4 v[16:19], v[8:9], off offset:16
	global_load_dwordx4 v[20:23], v[8:9], off
	global_load_dwordx4 v[0:3], v[8:9], off offset:1040
	s_nop 0
	global_load_dwordx4 v[8:11], v[8:9], off offset:1024
	v_mad_i64_i32 v[32:33], s[26:27], v64, s37, v[60:61]
	global_load_dwordx2 v[48:49], v[32:33], off offset:2048
	v_sub_f32_e32 v15, v34, v75
	v_mul_f32_e32 v15, 0x3fb8aa3b, v15
	v_exp_f32_e32 v54, v15
	s_add_i32 s50, s50, 1
	v_lshl_add_u64 v[62:63], v[62:63], 0, s[22:23]
	v_add_u32_e32 v64, 64, v64
	s_cmp_lg_u32 s50, 31
	v_add_u32_e32 v66, 64, v66
	s_cbranch_scc0 .LBB0_665

.LBB0_663:
	s_or_b64 exec, exec, s[26:27]
	v_mul_f32_e32 v15, v35, v32
	v_cvt_pk_bf16_f32 v15, v15, s0
	ds_write_b16 v36, v15 offset:432
	ds_read_b128 v[32:35], v68
	ds_read_b128 v[90:93], v44
	ds_read_b128 v[94:97], v68 offset:64
	ds_read_b128 v[98:101], v44 offset:64
	ds_read_b128 v[102:105], v68 offset:128
	ds_read_b128 v[106:109], v44 offset:128
	ds_read_b128 v[110:113], v44 offset:192
	s_waitcnt lgkmcnt(5)
	v_mfma_f32_16x16x32_bf16 v[32:35], v[32:35], v[90:93], 0
	s_mulk_i32 s51, 0x1b00
	v_lshlrev_b32_e32 v15, 1, v52
	s_add_i32 s26, s51, 0
	s_waitcnt lgkmcnt(3)
	v_mfma_f32_16x16x32_bf16 v[32:35], v[94:97], v[98:101], v[32:35]
	ds_read_b128 v[94:97], v68 offset:192
	ds_read_b128 v[118:121], v70 offset:34816
	v_add3_u32 v15, s26, v15, v82
	s_waitcnt lgkmcnt(3)
	v_mfma_f32_16x16x32_bf16 v[32:35], v[102:105], v[106:109], v[32:35]
	ds_read_b128 v[102:105], v15 offset:53248
	ds_read_b128 v[114:117], v71 offset:34816
	v_pk_mul_f32 v[30:31], v[54:55], v[30:31] op_sel_hi:[0,1]
	v_pk_mul_f32 v[28:29], v[54:55], v[28:29] op_sel_hi:[0,1]
	s_waitcnt lgkmcnt(3)
	v_mfma_f32_16x16x32_bf16 v[32:35], v[94:97], v[110:113], v[32:35]
	ds_read_b128 v[94:97], v15 offset:53312
	v_pk_mul_f32 v[26:27], v[54:55], v[26:27] op_sel_hi:[0,1]
	v_pk_mul_f32 v[24:25], v[54:55], v[24:25] op_sel_hi:[0,1]
	s_waitcnt lgkmcnt(1)
	v_mfma_f32_16x16x32_bf16 v[28:31], v[102:105], v[114:117], v[28:31]
	ds_read_b128 v[102:105], v15 offset:55552
	v_pk_mul_f32 v[6:7], v[54:55], v[6:7] op_sel_hi:[0,1]
	v_pk_mul_f32 v[4:5], v[54:55], v[4:5] op_sel_hi:[0,1]
	s_waitcnt lgkmcnt(1)
	v_mfma_f32_16x16x32_bf16 v[28:31], v[94:97], v[118:121], v[28:31]
	ds_read_b128 v[94:97], v15 offset:55616
	v_ashrrev_i32_e32 v67, 31, v66
	s_waitcnt vmcnt(5)
	v_readlane_b32 s51, v12, 63
	s_waitcnt lgkmcnt(1)
	v_mfma_f32_16x16x32_bf16 v[24:27], v[102:105], v[114:117], v[24:27]
	ds_read_b128 v[102:105], v15 offset:57856
	ds_read_b128 v[122:125], v57
	v_readlane_b32 s52, v14, 63
	s_waitcnt lgkmcnt(2)
	v_mfma_f32_16x16x32_bf16 v[24:27], v[94:97], v[118:121], v[24:27]
	ds_read_b128 v[94:97], v15 offset:57920
	s_waitcnt lgkmcnt(2)
	v_mfma_f32_16x16x32_bf16 v[4:7], v[102:105], v[114:117], v[4:7]
	ds_read_b128 v[102:105], v57 offset:64
	v_add3_u32 v15, s26, v81, v80
	s_waitcnt lgkmcnt(2)
	v_mfma_f32_16x16x32_bf16 v[90:93], v[122:125], v[90:93], 0
	ds_read_b128 v[114:117], v57 offset:128
	ds_read_b128 v[122:125], v57 offset:192
	s_waitcnt lgkmcnt(0)
	s_barrier
	s_waitcnt lgkmcnt(2)
	v_mfma_f32_16x16x32_bf16 v[90:93], v[102:105], v[98:101], v[90:93]
	ds_read_b128 v[98:101], v15 offset:57856
	s_waitcnt lgkmcnt(2)
	v_mfma_f32_16x16x32_bf16 v[90:93], v[114:117], v[106:109], v[90:93]
	ds_read_b128 v[102:105], v15 offset:57920
	ds_read_b128 v[106:109], v55
	ds_read_b128 v[114:117], v55 offset:64
	v_add_u32_e32 v15, v15, v79
	s_waitcnt lgkmcnt(1)
	v_mfma_f32_16x16x32_bf16 v[98:101], v[98:101], v[106:109], 0
	s_waitcnt lgkmcnt(0)
	v_mfma_f32_16x16x32_bf16 v[98:101], v[102:105], v[114:117], v[98:101]
	ds_read_b128 v[102:105], v15 offset:53248
	ds_read_b128 v[126:129], v15 offset:53312
	v_lshl_add_u32 v15, v47, 2, s25
	ds_read2st64_b32 v[130:131], v15 offset0:2 offset1:3
	v_mfma_f32_16x16x32_bf16 v[90:93], v[122:125], v[110:113], v[90:93]
	s_and_b32 s25, s50, 1
	s_waitcnt lgkmcnt(0)
	v_max_f32_e32 v54, v131, v131
	v_mfma_f32_16x16x32_bf16 v[4:7], v[94:97], v[118:121], v[4:7]
	s_nop 3
	v_fma_f32 v15, v130, v90, v98
	v_max_f32_e64 v15, |v15|, v54
	v_rcp_f32_e32 v90, v15
	v_fma_f32 v15, v130, v91, v99
	v_max_f32_e64 v15, |v15|, v54
	v_rcp_f32_e32 v91, v15
	v_fma_f32 v15, v130, v92, v100
	v_max_f32_e64 v15, |v15|, v54
	v_fmac_f32_e32 v101, v130, v93
	v_rcp_f32_e32 v92, v15
	v_max_f32_e64 v15, |v101|, v54
	v_mfma_f32_16x16x32_bf16 v[94:97], v[102:105], v[106:109], 0
	v_rcp_f32_e32 v93, v15
	v_cvt_pk_bf16_f32 v15, v28, s0
	ds_write_b16 v45, v15
	v_cvt_pk_bf16_f32 v15, v29, s0
	ds_write_b16 v45, v15 offset:272
	v_cvt_pk_bf16_f32 v15, v30, s0
	ds_write_b16 v45, v15 offset:544
	v_cvt_pk_bf16_f32 v15, v31, s0
	v_mfma_f32_16x16x32_bf16 v[94:97], v[126:129], v[114:117], v[94:97]
	ds_write_b16 v45, v15 offset:816
	v_cvt_pk_bf16_f32 v15, v24, s0
	ds_write_b16 v45, v15 offset:4352
	v_cvt_pk_bf16_f32 v15, v25, s0
	ds_write_b16 v45, v15 offset:4624
	v_cvt_pk_bf16_f32 v15, v26, s0
	ds_write_b16 v45, v15 offset:4896
	v_cvt_pk_bf16_f32 v15, v27, s0
	v_pk_fma_f32 v[32:33], v[32:33], v[130:131], v[94:95] op_sel_hi:[1,0,1]
	v_pk_fma_f32 v[34:35], v[34:35], v[130:131], v[96:97] op_sel_hi:[1,0,1]
	ds_write_b16 v45, v15 offset:5168
	v_cvt_pk_bf16_f32 v15, v4, s0
	v_pk_mul_f32 v[32:33], v[32:33], v[90:91]
	v_pk_mul_f32 v[34:35], v[34:35], v[92:93]
	ds_write_b16 v45, v15 offset:8704
	v_cvt_pk_bf16_f32 v15, v5, s0
	v_cvt_pk_bf16_f32 v32, v32, v33
	v_cvt_pk_bf16_f32 v33, v34, v35
	v_lshlrev_b64 v[34:35], 11, v[66:67]
	ds_write_b16 v45, v15 offset:8976
	v_cvt_pk_bf16_f32 v15, v6, s0
	v_lshl_add_u64 v[34:35], v[50:51], 0, v[34:35]
	ds_write_b16 v45, v15 offset:9248
	v_cvt_pk_bf16_f32 v15, v7, s0
	global_store_dwordx2 v[34:35], v[32:33], off
	ds_write_b16 v45, v15 offset:9520
	s_and_saveexec_b64 s[26:27], s[8:9]
	s_cbranch_execz .LBB0_642
	v_add_f32_e32 v33, v75, v12
	v_add_f32_e32 v14, v12, v14
	v_max_f32_e32 v14, v33, v14
	v_sub_f32_e32 v33, v33, v14
	s_lshl_b32 s53, s25, 10
	v_mul_f32_e32 v33, 0x3fb8aa3b, v33
	s_add_i32 s53, s53, 0
	v_mul_f32_e32 v34, 0xbfb8aa3b, v14
	v_exp_f32_e32 v33, v33
	s_add_i32 s53, s53, 0x15d00
	v_exp_f32_e32 v34, v34
	v_lshl_add_u32 v32, v46, 2, s53
	v_sub_f32_e32 v12, v12, v14
	v_lshl_add_u32 v15, v69, 2, s53
	ds_write_b32 v32, v12
	ds_write2st64_b32 v15, v13, v33 offset0:1 offset1:2
	ds_write_b32 v15, v34 offset:768
	s_branch .LBB0_642

.LBB0_685:
	s_or_b64 exec, exec, s[26:27]
	v_mul_f32_e32 v32, v35, v32
	v_cvt_pk_bf16_f32 v32, v32, s0
	ds_write_b16 v36, v32 offset:432
	ds_read_b128 v[32:35], v68
	s_waitcnt lgkmcnt(5)
	ds_read_b128 v[62:65], v44
	ds_read_b128 v[84:87], v68 offset:64
	ds_read_b128 v[88:91], v44 offset:64
	ds_read_b128 v[92:95], v68 offset:128
	v_lshl_add_u32 v52, v52, 1, 0
	v_pk_mul_f32 v[30:31], v[54:55], v[30:31] op_sel_hi:[0,1]
	s_waitcnt lgkmcnt(3)
	v_mfma_f32_16x16x32_bf16 v[96:99], v[32:35], v[62:65], 0
	v_add_u32_e32 v32, v52, v82
	ds_read_b128 v[100:103], v44 offset:128
	ds_read_b128 v[104:107], v32 offset:53248
	v_pk_mul_f32 v[28:29], v[54:55], v[28:29] op_sel_hi:[0,1]
	s_waitcnt lgkmcnt(3)
	v_mfma_f32_16x16x32_bf16 v[82:85], v[84:87], v[88:91], v[96:99]
	s_nop 2
	ds_read_b128 v[96:99], v68 offset:192
	ds_read_b128 v[108:111], v44 offset:192
	ds_read_b128 v[112:115], v71 offset:34816
	v_pk_mul_f32 v[26:27], v[54:55], v[26:27] op_sel_hi:[0,1]
	v_pk_mul_f32 v[24:25], v[54:55], v[24:25] op_sel_hi:[0,1]
	s_waitcnt lgkmcnt(4)
	v_mfma_f32_16x16x32_bf16 v[82:85], v[92:95], v[100:103], v[82:85]
	ds_read_b128 v[92:95], v32 offset:53312
	ds_read_b128 v[116:119], v70 offset:34816
	v_add3_u32 v34, 0, v81, v80
	v_lshl_add_u32 v52, v47, 2, s38
	s_waitcnt lgkmcnt(2)
	v_mfma_f32_16x16x32_bf16 v[28:31], v[104:107], v[112:115], v[28:31]
	v_add_u32_e32 v35, v34, v79
	v_pk_mul_f32 v[6:7], v[54:55], v[6:7] op_sel_hi:[0,1]
	v_pk_mul_f32 v[4:5], v[54:55], v[4:5] op_sel_hi:[0,1]
	v_mfma_f32_16x16x32_bf16 v[82:85], v[96:99], v[108:111], v[82:85]
	ds_read_b128 v[96:99], v32 offset:55552
	v_add_u32_e32 v33, s49, v47
	s_waitcnt vmcnt(5)
	v_readlane_b32 s25, v12, 63
	s_waitcnt lgkmcnt(1)
	v_mfma_f32_16x16x32_bf16 v[28:31], v[92:95], v[116:119], v[28:31]
	ds_read_b128 v[92:95], v32 offset:55616
	v_readlane_b32 s49, v14, 63
	s_waitcnt lgkmcnt(1)
	v_mfma_f32_16x16x32_bf16 v[24:27], v[96:99], v[112:115], v[24:27]
	ds_read_b128 v[96:99], v57
	s_waitcnt lgkmcnt(1)
	v_mfma_f32_16x16x32_bf16 v[24:27], v[92:95], v[116:119], v[24:27]
	ds_read_b128 v[92:95], v57 offset:64
	s_waitcnt lgkmcnt(1)
	v_mfma_f32_16x16x32_bf16 v[62:65], v[96:99], v[62:65], 0
	ds_read_b128 v[96:99], v57 offset:128
	ds_read_b128 v[104:107], v57 offset:192
	ds_read_b128 v[120:123], v32 offset:57856
	ds_read_b128 v[124:127], v32 offset:57920
	s_waitcnt lgkmcnt(0)
	s_barrier
	s_waitcnt lgkmcnt(4)
	v_mfma_f32_16x16x32_bf16 v[62:65], v[92:95], v[88:91], v[62:65]
	ds_read_b128 v[86:89], v34 offset:57856
	s_waitcnt lgkmcnt(4)
	v_mfma_f32_16x16x32_bf16 v[62:65], v[96:99], v[100:103], v[62:65]
	ds_read_b128 v[90:93], v34 offset:57920
	ds_read_b128 v[94:97], v55
	ds_read_b128 v[98:101], v55 offset:64
	ds_read2st64_b32 v[66:67], v52 offset0:2 offset1:3
	s_waitcnt lgkmcnt(0)
	v_max_f32_e32 v54, v67, v67
	v_mfma_f32_16x16x32_bf16 v[86:89], v[86:89], v[94:97], 0
	v_mfma_f32_16x16x32_bf16 v[86:89], v[90:93], v[98:101], v[86:89]
	v_mfma_f32_16x16x32_bf16 v[62:65], v[104:107], v[108:111], v[62:65]
	ds_read_b128 v[90:93], v35 offset:53248
	ds_read_b128 v[102:105], v35 offset:53312
	s_waitcnt lgkmcnt(1)
	v_mfma_f32_16x16x32_bf16 v[90:93], v[90:93], v[94:97], 0
	s_nop 3
	v_fma_f32 v52, v66, v62, v86
	v_max_f32_e64 v52, |v52|, v54
	v_rcp_f32_e32 v62, v52
	v_fma_f32 v52, v66, v63, v87
	v_max_f32_e64 v52, |v52|, v54
	v_rcp_f32_e32 v63, v52
	v_fma_f32 v52, v66, v64, v88
	v_max_f32_e64 v52, |v52|, v54
	v_fmac_f32_e32 v89, v66, v65
	v_rcp_f32_e32 v64, v52
	s_waitcnt lgkmcnt(0)
	v_mfma_f32_16x16x32_bf16 v[90:93], v[102:105], v[98:101], v[90:93]
	v_max_f32_e64 v52, |v89|, v54
	v_rcp_f32_e32 v65, v52
	v_mfma_f32_16x16x32_bf16 v[4:7], v[120:123], v[112:115], v[4:7]
	v_mfma_f32_16x16x32_bf16 v[4:7], v[124:127], v[116:119], v[4:7]
	s_nop 3
	v_fma_f32 v80, v82, v66, v90
	v_fma_f32 v81, v83, v66, v91
	v_pk_fma_f32 v[66:67], v[84:85], v[66:67], v[92:93] op_sel_hi:[1,0,1]
	v_pk_mul_f32 v[62:63], v[80:81], v[62:63]
	v_pk_mul_f32 v[64:65], v[66:67], v[64:65]
	v_cvt_pk_bf16_f32 v62, v62, v63
	v_cvt_pk_bf16_f32 v63, v64, v65
	v_add_u32_e32 v64, 0x780, v33
	v_ashrrev_i32_e32 v65, 31, v64
	v_lshlrev_b64 v[64:65], 11, v[64:65]
	v_lshl_add_u64 v[50:51], v[50:51], 0, v[64:65]
	global_store_dwordx2 v[50:51], v[62:63], off
	v_cvt_pk_bf16_f32 v50, v28, s0
	ds_write_b16 v45, v50
	v_cvt_pk_bf16_f32 v50, v29, s0
	ds_write_b16 v45, v50 offset:272
	v_cvt_pk_bf16_f32 v50, v30, s0
	ds_write_b16 v45, v50 offset:544
	v_cvt_pk_bf16_f32 v50, v31, s0
	ds_write_b16 v45, v50 offset:816
	v_cvt_pk_bf16_f32 v50, v24, s0
	ds_write_b16 v45, v50 offset:4352
	v_cvt_pk_bf16_f32 v50, v25, s0
	ds_write_b16 v45, v50 offset:4624
	v_cvt_pk_bf16_f32 v50, v26, s0
	ds_write_b16 v45, v50 offset:4896
	v_cvt_pk_bf16_f32 v50, v27, s0
	ds_write_b16 v45, v50 offset:5168
	v_cvt_pk_bf16_f32 v50, v4, s0
	ds_write_b16 v45, v50 offset:8704
	v_cvt_pk_bf16_f32 v50, v5, s0
	ds_write_b16 v45, v50 offset:8976
	v_cvt_pk_bf16_f32 v50, v6, s0
	ds_write_b16 v45, v50 offset:9248
	v_cvt_pk_bf16_f32 v50, v7, s0
	ds_write_b16 v45, v50 offset:9520
	s_and_saveexec_b64 s[26:27], s[8:9]
	s_cbranch_execz .LBB0_687
	v_add_f32_e32 v51, v75, v12
	v_add_f32_e32 v14, v12, v14
	v_max_f32_e32 v14, v51, v14
	v_sub_f32_e32 v51, v51, v14
	v_mul_f32_e32 v51, 0x3fb8aa3b, v51
	v_mul_f32_e32 v52, 0xbfb8aa3b, v14
	v_exp_f32_e32 v51, v51
	v_exp_f32_e32 v52, v52
	v_lshl_add_u32 v46, v46, 2, s47
	v_sub_f32_e32 v12, v12, v14
	v_lshl_add_u32 v50, v69, 2, s47
	ds_write_b32 v46, v12
	ds_write2st64_b32 v50, v13, v51 offset0:1 offset1:2
	ds_write_b32 v50, v52 offset:768
